# LRU conv stage: wait for the conv-weight loads moved after the bias load issue (one global round trip instead of two)
# speedup vs baseline: 1.0118x; 1.0030x over previous
; __device__ __forceinline__ float bf2f(unsigned short b) { return __uint_as_float(((unsigned)b) << 16); }
; __device__ __forceinline__ void mixer_pre_item(int item, const float* const* in, int l, unsigned char* ws, LAS unsigned char* lds, int tid, int lane, int wave) {
;     ...
;     {
;         const int ch = tid & 255, t0 = (tid >> 8) * 16;
;         const float* cw = in[8] + (size_t)l * 4 * 256;
;         const float w0 = cw[ch], w1 = cw[256 + ch], w2 = cw[512 + ch], w3 = cw[768 + ch], bb = in[9][l * 256 + ch];
;         float xm3 = bf2f(STGL[t0 * 256 + ch]), xm2 = bf2f(STGL[(t0 + 1) * 256 + ch]), xm1 = bf2f(STGL[(t0 + 2) * 256 + ch]);
.LBB0_639:
	s_or_b64 exec, exec, s[38:39]
	v_lshlrev_b32_sdwa v12, v233, v34 dst_sel:DWORD dst_unused:UNUSED_PAD src0_sel:DWORD src1_sel:BYTE_0
	v_readlane_b32 s40, v249, 62
	s_barrier
	global_load_dword v4, v12, s[12:13]
	global_load_dword v5, v12, s[12:13] offset:1024
	global_load_dword v6, v12, s[12:13] offset:2048
	global_load_dword v7, v12, s[12:13] offset:3072
	v_or_b32_sdwa v0, v34, s1 dst_sel:DWORD dst_unused:UNUSED_PAD src0_sel:BYTE_0 src1_sel:DWORD
	v_readlane_b32 s42, v248, 0
	v_readlane_b32 s43, v248, 1
	v_lshlrev_b32_sdwa v8, v161, v34 dst_sel:DWORD dst_unused:UNUSED_PAD src0_sel:DWORD src1_sel:BYTE_0
	s_movk_i32 s21, 0x2100
	v_lshl_add_u64 v[2:3], v[0:1], 2, s[42:43]
	global_load_dword v0, v[2:3], off
	v_ashrrev_i32_e32 v2, 4, v34
	v_lshlrev_b32_e32 v3, 9, v2
	v_and_b32_e32 v3, 0xffffe000, v3
	v_add3_u32 v3, 0, v3, v8
	ds_read_u16 v9, v3
	ds_read_u16 v10, v3 offset:1024
	ds_read_u16 v3, v3 offset:512
	v_lshrrev_b32_e32 v13, 4, v2
	v_readlane_b32 s34, v250, 15
	s_waitcnt lgkmcnt(2)
	v_lshlrev_b32_e32 v11, 16, v9
	s_waitcnt lgkmcnt(1)
	v_lshlrev_b32_e32 v9, 16, v10
	s_waitcnt lgkmcnt(0)
	v_lshlrev_b32_e32 v10, 16, v3
	v_mad_u64_u32 v[2:3], s[30:31], v13, s21, v[8:9]
	v_lshl_or_b32 v3, v13, 14, v12
	v_lshlrev_b32_e32 v12, 13, v13
	s_movk_i32 s21, 0x600
	s_mov_b32 s20, 16
	v_add_u32_e32 v3, 0x4600, v3
	v_or3_b32 v8, v12, v8, s21
	v_readlane_b32 s35, v250, 16
	v_readlane_b32 s41, v249, 63
	s_waitcnt vmcnt(0)
